# HGRN pass 1: next chunk's z/v tiles via 4 whole-row loads + LDS tile + 8 transposed reads instead of 32 two-byte loads per lane; plus rotary-row prefetch in the P1 epilogue
# speedup vs baseline: 1.0009x; 1.0009x over previous
.LBB0_329:
	s_waitcnt lgkmcnt(0)
	s_barrier
	ds_read_b128 v[54:57], v87 offset:60928
	v_add_u32_e32 v48, s23, v81
	ds_read_b128 v[58:61], v48
	ds_read_b128 v[62:65], v88
	ds_read_b128 v[66:69], v87 offset:60992
	s_add_i32 s22, s22, 64
	s_sub_i32 s24, s24, 64
	s_waitcnt lgkmcnt(2)
	v_pk_mul_f32 v[32:33], v[32:33], v[58:59]
	v_pk_mul_f32 v[34:35], v[34:35], v[60:61]
	v_pk_mul_f32 v[24:25], v[24:25], v[58:59]
	v_pk_mul_f32 v[26:27], v[26:27], v[60:61]
	s_waitcnt lgkmcnt(1)
	v_mfma_f32_16x16x32_bf16 v[32:35], v[54:57], v[62:65], v[32:35]
	ds_read_b128 v[62:65], v88 offset:64
	ds_read_b128 v[92:95], v88 offset:2304
	v_pk_mul_f32 v[28:29], v[28:29], v[58:59]
	v_pk_mul_f32 v[30:31], v[30:31], v[60:61]
	s_waitcnt lgkmcnt(1)
	v_mfma_f32_16x16x32_bf16 v[32:35], v[66:69], v[62:65], v[32:35]
	v_mul_f32_e64 v36, v36, v58
	v_mul_f32_e64 v37, v37, v59
	v_pk_mul_f32 v[38:39], v[38:39], v[60:61]
	v_pk_mul_f32 v[16:17], v[16:17], v[58:59]
	s_waitcnt lgkmcnt(0)
	v_mfma_f32_16x16x32_bf16 v[24:27], v[54:57], v[92:95], v[24:27]
	ds_read_b128 v[62:65], v88 offset:2368
	ds_read_b128 v[92:95], v88 offset:4608
	v_pk_mul_f32 v[18:19], v[18:19], v[60:61]
	v_pk_mul_f32 v[12:13], v[12:13], v[58:59]
	s_waitcnt lgkmcnt(1)
	v_mfma_f32_16x16x32_bf16 v[24:27], v[66:69], v[62:65], v[24:27]
	v_mul_f32_e64 v14, v14, v60
	v_mul_f32_e64 v15, v15, v61
	v_pk_mul_f32 v[8:9], v[8:9], v[58:59]
	v_pk_mul_f32 v[10:11], v[10:11], v[60:61]
	s_waitcnt lgkmcnt(0)
	v_mfma_f32_16x16x32_bf16 v[28:31], v[54:57], v[92:95], v[28:31]
	ds_read_b128 v[62:65], v88 offset:4672
	ds_read_b128 v[92:95], v89
	ds_read_b128 v[96:99], v88 offset:9216
	v_pk_mul_f32 v[20:21], v[20:21], v[58:59]
	v_pk_mul_f32 v[22:23], v[22:23], v[60:61]
	s_waitcnt lgkmcnt(2)
	v_mfma_f32_16x16x32_bf16 v[28:31], v[66:69], v[62:65], v[28:31]
	ds_read_b128 v[62:65], v88 offset:13888
	v_mul_f32_e32 v76, v76, v70
	s_cmpk_eq_i32 s22, 0x400
	s_waitcnt lgkmcnt(2)
	v_mfma_f32_16x16x32_bf16 v[36:39], v[54:57], v[92:95], v[36:39]
	ds_read_b128 v[92:95], v89 offset:64
	ds_read_b128 v[100:103], v90
	s_waitcnt lgkmcnt(1)
	v_mfma_f32_16x16x32_bf16 v[36:39], v[66:69], v[92:95], v[36:39]
	v_mfma_f32_16x16x32_bf16 v[16:19], v[54:57], v[96:99], v[16:19]
	ds_read_b128 v[92:95], v88 offset:9280
	ds_read_b128 v[96:99], v88 offset:11520
	s_waitcnt lgkmcnt(1)
	v_mfma_f32_16x16x32_bf16 v[16:19], v[66:69], v[92:95], v[16:19]
	s_waitcnt lgkmcnt(0)
	v_mfma_f32_16x16x32_bf16 v[12:15], v[54:57], v[96:99], v[12:15]
	ds_read_b128 v[92:95], v88 offset:11584
	ds_read_b128 v[96:99], v88 offset:13824
	ds_read_b128 v[58:61], v90 offset:64
	s_waitcnt lgkmcnt(0)
	v_mfma_f32_16x16x32_bf16 v[8:11], v[54:57], v[96:99], v[8:11]
	s_waitcnt vmcnt(0)
	ds_write_b128 v226, v[206:209]
	ds_write_b128 v226, v[210:213] offset:1280
	ds_write_b128 v226, v[214:217] offset:20480
	ds_write_b128 v226, v[218:221] offset:21760
	s_waitcnt lgkmcnt(0)
	s_barrier
	v_mfma_f32_16x16x32_bf16 v[20:23], v[54:57], v[100:103], v[20:23]
	v_mfma_f32_16x16x32_bf16 v[12:15], v[66:69], v[92:95], v[12:15]
	v_mfma_f32_16x16x32_bf16 v[8:11], v[66:69], v[62:65], v[8:11]
	v_mfma_f32_16x16x32_bf16 v[20:23], v[66:69], v[58:61], v[20:23]
	s_cbranch_scc1 .LBB0_342
	ds_read_b64_tr_b16 v[0:1], v227 offset:0
	ds_read_b64_tr_b16 v[2:3], v227 offset:1280
	ds_read_b64_tr_b16 v[4:5], v227 offset:2560
	ds_read_b64_tr_b16 v[6:7], v227 offset:3840
	ds_read_b64_tr_b16 v[44:45], v227 offset:20480
	ds_read_b64_tr_b16 v[46:47], v227 offset:21760
	ds_read_b64_tr_b16 v[40:41], v227 offset:23040
	ds_read_b64_tr_b16 v[42:43], v227 offset:24320
	s_waitcnt lgkmcnt(0)
.LBB0_330:
	v_and_b32_e32 v228, 63, v145
	v_lshrrev_b32_e32 v229, 4, v228
	s_lshl_b32 s40, s35, 3
	v_add_u32_e32 v226, s40, v229
	v_mul_u32_u24_e32 v226, 0x140, v226
	v_and_b32_e32 v225, 15, v228
	v_lshl_add_u32 v226, v225, 4, v226
	v_bfe_u32 v227, v228, 2, 2
	s_lshl_b32 s40, s36, 4
	v_add_u32_e32 v227, s40, v227
	v_mul_u32_u24_e32 v227, 0x140, v227
	v_lshl_add_u32 v227, v229, 5, v227
	v_and_b32_e32 v225, 3, v228
	v_lshl_add_u32 v227, v225, 3, v227
	s_and_b32 s40, s35, 1
	s_lshl_b32 s40, s40, 7
	v_add_u32_e32 v227, s40, v227
	s_cmpk_eq_i32 s22, 0x3c0
	s_cbranch_scc1 .Lp1_nopf
	s_add_i32 s40, s11, s22
	s_add_i32 s40, s40, 64
	s_add_i32 s41, s24, 15
	s_and_b64 s[42:43], s[12:13], exec
	s_cselect_b32 s40, s40, s41
	s_cselect_b32 s42, 1, -1
	s_and_b32 s44, s35, 1
	s_lshl_b32 s44, s44, 3
	s_mul_i32 s45, s44, s42
	s_add_i32 s40, s40, s45
	s_add_i32 s46, s42, -1
	s_ashr_i32 s46, s46, 1
	s_mul_i32 s45, s46, 3
	s_add_i32 s40, s40, s45
	s_and_b32 s46, s46, 3
	s_lshl_b32 s45, s42, 2
	s_add_i32 s41, s40, s45
	s_mul_i32 s40, s40, 0x1400
	s_mul_i32 s41, s41, 0x1400
	s_add_u32 s48, s82, s40
	s_addc_u32 s49, s83, 0
	s_add_u32 s40, s82, s41
	s_addc_u32 s41, s83, 0
	v_lshrrev_b32_e32 v224, 4, v81
	v_xor_b32_e32 v224, s46, v224
	v_mul_u32_u24_e32 v224, 0x1400, v224
	v_lshl_add_u32 v224, v78, 4, v224
	v_lshlrev_b32_e32 v225, 1, v75
	v_sub_u32_e32 v222, v85, v225
	v_add_u32_e32 v222, v222, v224
	v_sub_u32_e32 v223, v86, v225
	v_add_u32_e32 v223, v223, v224
	global_load_dwordx4 v[206:209], v222, s[48:49] nt
	global_load_dwordx4 v[210:213], v222, s[40:41] nt
	global_load_dwordx4 v[214:217], v223, s[48:49] offset:3072 nt
	global_load_dwordx4 v[218:221], v223, s[40:41] offset:3072 nt
